# v115 plus P0 small setup loops (forget tile, gate fragments, coef) moved to workgroups c+G/2
# baseline (speedup 1.0000x reference)
; __device__ __forceinline__ unsigned pk2(float lo, float hi) { return f2bf(lo) | (f2bf(hi) << 16); }
; __global__ void __launch_bounds__(NWAVES * 64, 2) hybrid_fwd(Args args) {
;     ...
;         const int gt = c * (NWAVES * 64) + tid, NGT = G * NWAVES * 64;
;         for (int e = gt; e < 256 * 128; e += NGT) { const int row = e >> 7, k8 = (e & 127) * 8; v4u o = (v4u){0u, 0u, 0u, 0u};
;             if (row < 16) { const float* s = args->w_in + (size_t)k8 * IN_COLS + 5120 + row;
;                 o.x = pk2(s[0], s[IN_COLS]); o.y = pk2(s[2 * IN_COLS], s[3 * IN_COLS]); o.z = pk2(s[4 * IN_COLS], s[5 * IN_COLS]); o.w = pk2(s[6 * IN_COLS], s[7 * IN_COLS]); }
;             *(v4u*)(WinT + (size_t)(NZC + row) * D + k8) = o; }
.LBB0_46:
	s_load_dword s6, s[0:1], 0xa8
	v_readlane_b32 s2, v255, 0
	s_waitcnt lgkmcnt(0)
	s_lshr_b32 s98, s6, 1
	s_add_i32 s98, s2, s98
	s_cmp_ge_u32 s98, s6
	s_cbranch_scc0 .Lp0_rc
	s_sub_i32 s98, s98, s6
.Lp0_rc:
	s_mov_b32 s2, s98
	s_nop 1
	v_lshl_add_u32 v8, s2, 9, v236
	s_load_dword s2, s[0:1], 0xa8
	s_waitcnt lgkmcnt(0)
	s_lshl_b32 s6, s2, 9
	s_mov_b32 s2, 0x8000
	v_cmp_gt_i32_e32 vcc, s2, v8
	s_and_saveexec_b64 s[8:9], vcc
	s_cbranch_execz .LBB0_51
	s_mov_b32 s2, s98
	s_mov_b64 s[22:23], 0
	v_mov_b32_e32 v11, 0
	v_lshl_add_u32 v1, s2, 12, v9
	s_load_dword s2, s[0:1], 0xa8
	s_movk_i32 s3, 0x7fff
	s_mov_b32 s7, 0xffff0000
	v_mov_b32_e32 v9, v8
	s_waitcnt lgkmcnt(0)
	s_lshl_b32 s2, s2, 12
	s_branch .LBB0_49
